# conv: static s_setprio 1 for waves 0-3 over the convolution items (other-half A/B of the earlier waves 4-7 test)
# speedup vs baseline: 1.0028x; 1.0001x over previous
.LBB0_905:
	s_setprio 0
	s_cmp_eq_u32 s100, 2
	s_cbranch_scc1 .LBB0_945
	s_cmp_lt_i32 s92, 6
	s_cselect_b64 s[4:5], -1, 0
	s_cmpk_lt_i32 s20, 0x200
	s_cselect_b64 s[0:1], -1, 0
	s_and_b64 s[4:5], s[4:5], s[0:1]
	s_and_b64 s[2:3], s[4:5], s[2:3]
	s_andn2_b64 vcc, exec, s[2:3]
	s_cbranch_vccnz .LBB0_945
	v_readfirstlane_b32 s99, v160
	s_nop 3
	s_lshr_b32 s99, s99, 8
	s_cmp_eq_u32 s99, 0
	s_cbranch_scc0 .Lcv_prio_done
	s_setprio 1
.Lcv_prio_done:
	s_waitcnt vmcnt(0)
	v_or_b32_e32 v1, 0x400, v160
	v_sub_u32_e32 v4, 0x1010, v1
	v_or_b32_e32 v1, 0x800, v160
	v_sub_u32_e32 v8, 0x1010, v1
	v_or_b32_e32 v1, 0xc00, v160
	v_sub_u32_e32 v12, 0x1010, v1
	v_sub_u32_e32 v1, 0x210, v160
	v_sub_u32_e32 v3, 0, v1
	s_movk_i32 s2, 0x211
	v_max_i32_e32 v162, v1, v3
	v_mov_b32_e32 v1, 0x800000
	v_cmp_gt_u32_e32 vcc, s2, v160
	v_or_b32_e32 v3, 0x1000, v160
	s_movk_i32 s2, 0x1011
	v_cndmask_b32_e64 v164, v1, 0, vcc
	v_cmp_gt_u32_e32 vcc, s2, v3
	v_sub_u32_e32 v5, 0x1010, v3
	s_movk_i32 s10, 0x2018
	v_cndmask_b32_e64 v168, v1, 0, vcc
	v_or_b32_e32 v1, 0x2000, v160
	v_sub_u32_e32 v7, 0, v5
	v_cmp_gt_u32_e64 s[10:11], s10, v1
	v_lshrrev_b32_e32 v1, 5, v160
	v_max_i32_e32 v166, v5, v7
	v_and_b32_e32 v5, 31, v160
	v_and_b32_e32 v9, 30, v1
	v_mul_i32_i24_e32 v11, 0xffffff00, v9
	v_lshlrev_b32_e32 v170, 3, v5
	v_sub_u32_e32 v3, 0x1010, v160
	v_bfe_u32 v7, v160, 5, 1
	v_sub_u32_e32 v11, v11, v170
	v_mov_b32_e32 v0, 0
	v_min_u32_e32 v18, 0xfff, v3
	v_bfe_u32 v3, v160, 5, 3
	v_lshlrev_b32_e32 v13, 4, v7
	v_lshlrev_b32_e32 v11, 1, v11
	s_movk_i32 s12, 0x410
	v_lshlrev_b32_e32 v20, 13, v3
	v_mov_b32_e32 v21, v0
	v_add3_u32 v201, 0, v11, v13
	v_and_b32_e32 v11, 7, v160
	s_add_u32 s42, s22, 0x1cb6000
	v_mad_u32_u24 v196, v5, s12, v13
	v_lshl_add_u64 v[20:21], s[22:23], 0, v[20:21]
	s_mov_b64 s[12:13], 0x194bc000
	v_lshlrev_b32_e32 v13, 9, v160
	v_lshlrev_b32_e32 v24, 1, v11
	v_mov_b32_e32 v25, v0
	s_addc_u32 s43, s23, 0
	v_lshl_add_u64 v[174:175], v[20:21], 0, s[12:13]
	s_movk_i32 s26, 0x2080
	v_and_b32_e32 v20, 0x3000, v13
	v_lshlrev_b32_e32 v22, 5, v7
	v_lshl_add_u64 v[24:25], s[22:23], 0, v[24:25]
	s_mov_b64 s[28:29], 0x1b4bc000
	v_mov_b32_e32 v7, 0x100
	s_add_u32 s44, s22, 0x2cb6000
	v_sub_u32_e32 v2, 0xe10, v160
	v_sub_u32_e32 v6, 0xa10, v160
	v_sub_u32_e32 v10, 0x610, v160
	s_movk_i32 s8, 0x20f
	v_min_u32_e32 v14, 0x20f, v160
	v_min_u32_e32 v16, 15, v160
	s_movk_i32 s6, 0x218
	v_cmp_lt_u32_e64 s[12:13], 1, v5
	v_cmp_ne_u32_e64 s[14:15], 0, v5
	s_movk_i32 s16, 0xff
	v_mul_u32_u24_e32 v197, 0x2080, v3
	v_mad_u32_u24 v3, v3, s26, 0
	v_lshlrev_b32_e32 v198, 4, v5
	v_mad_u32_u24 v5, v1, s26, 0
	v_lshl_add_u64 v[176:177], v[24:25], 0, s[28:29]
	v_lshlrev_b32_e32 v24, 8, v9
	v_or_b32_e32 v26, 0x4000, v20
	v_lshl_or_b32 v28, v1, 8, v7
	s_addc_u32 s45, s23, 0
	s_mov_b32 s27, 0
	s_mov_b32 s46, 0x800000
	v_mov_b32_e32 v165, v0
	v_mov_b32_e32 v163, v0
	s_movk_i32 s47, 0x1000
	v_mov_b32_e32 v169, v0
	v_mov_b32_e32 v167, v0
	v_mov_b32_e32 v161, v0
	v_cmp_lt_u32_e64 s[2:3], 15, v160
	v_cmp_gt_u32_e64 s[4:5], 17, v160
	v_lshl_add_u32 v171, v160, 1, 0
	v_cmp_gt_u32_e64 s[6:7], s6, v160
	v_cmp_lt_u32_e64 s[8:9], s8, v160
	v_add_u32_e32 v172, -16, v170
	v_mov_b32_e32 v173, v0
	v_cmp_lt_u32_e64 s[16:17], s16, v160
	v_mul_u32_u24_e32 v199, 0x2080, v1
	v_add_u32_e32 v200, 0x3f0, v170
	v_lshlrev_b32_e32 v202, 2, v2
	v_lshlrev_b32_e32 v203, 2, v4
	v_lshlrev_b32_e32 v204, 2, v6
	v_lshlrev_b32_e32 v205, 2, v8
	v_lshlrev_b32_e32 v206, 2, v10
	v_lshlrev_b32_e32 v207, 2, v12
	s_mov_b32 s48, 0x801000
	s_mov_b32 s49, 0x802000
	v_lshlrev_b32_e32 v178, 2, v16
	v_lshlrev_b32_e32 v208, 2, v18
	s_movk_i32 s52, 0x7fff
	v_lshlrev_b32_e32 v180, 2, v14
	v_add_u32_e32 v209, v3, v198
	s_mov_b32 s53, 0x1000706
	v_add_u32_e32 v210, v5, v198
	s_movk_i32 s54, 0xff8
	s_movk_i32 s55, 0xf00
	s_movk_i32 s56, 0xef8
	v_lshlrev_b32_e32 v182, 1, v24
	v_lshlrev_b32_e32 v184, 1, v20
	v_lshlrev_b32_e32 v186, 1, v22
	v_lshlrev_b32_e32 v188, 1, v26
	v_lshlrev_b32_e32 v190, 1, v28
	v_mov_b32_e32 v179, v0
	s_mov_b32 s38, s20
	s_branch .LBB0_908

.LBB0_945:
	s_setprio 0
	s_cmp_lg_u32 s100, 1
	s_cbranch_scc1 .Lp6_join0
	s_mov_b32 s100, 2
	v_readlane_b32 s54, v254, 0
	v_readlane_b32 s55, v254, 1
	v_readlane_b32 s56, v254, 2
	v_readlane_b32 s57, v254, 3
	s_waitcnt vmcnt(0) lgkmcnt(0)
	s_barrier
	s_nop 4
	s_branch .Lp6_retout_entry
